# ACBD2
# speedup vs baseline: 1.0265x; 1.0028x over previous
;     ...
;   const int ntn = Npad / 256, ntk = K / 64;
;   const int total = (it_end < 0) ? ntn * ntk : it_end;
;   if (bid < 0) { bid = blockIdx.x; nb = gridDim.x; }
;   const int tid = opaque_tid();
;   for (int it = it_begin + bid; it < total; it += nb) {
;     const int tn = it % ntn, tk = it / ntn;
.Lwo_part:
	s_sub_i32 s98, s2, s44
	s_sub_i32 s99, s18, s44
	s_cmpk_gt_i32 s98, 0x3ff
	s_cbranch_scc1 .Lwo_done
	s_lshl_b32 s100, s99, 8
	s_mov_b32 s12, 1
	s_mov_b32 s13, 0
	s_movk_i32 s59, 0x404
	s_mov_b64 s[42:43], 0xf400000
	s_movk_i32 s60, 0x1000
	v_mov_b32_e32 v35, 0
	s_mov_b64 s[44:45], s[0:1]
	v_mov_b32_e32 v2, v254
	s_load_dwordx2 s[46:47], s[44:45], 0x68
	s_nop 0
	s_load_dwordx2 s[44:45], s[44:45], 0x48
	s_lshl_b64 s[48:49], s[12:13], 25
	v_lshlrev_b32_e32 v1, 2, v2
	v_and_b32_e32 v1, 0xfc, v1
	s_waitcnt lgkmcnt(0)
	s_add_u32 s46, s46, s48
	s_addc_u32 s47, s47, s49
	s_lshl_b64 s[48:49], s[12:13], 26
	s_add_u32 s44, s44, s48
	v_lshlrev_b32_e32 v4, 3, v2
	s_addc_u32 s45, s45, s49
	v_lshlrev_b32_e32 v34, 2, v1
	v_and_b32_e32 v4, 56, v4
	v_lshl_add_u64 v[36:37], s[44:45], 0, v[34:35]
	v_add_u32_e32 v3, 16, v34
	v_lshlrev_b32_e32 v34, 1, v4
	v_add_u32_e32 v8, 0x800, v2
	v_mad_u32_u24 v6, v4, s59, 16
	v_lshl_add_u64 v[4:5], s[46:47], 0, v[34:35]
	v_ashrrev_i32_e32 v47, 6, v8
	v_add_u32_e32 v8, 0xa00, v2
	v_lshl_add_u64 v[38:39], v[4:5], 0, s[42:43]
	v_ashrrev_i32_e32 v34, 3, v2
	v_ashrrev_i32_e32 v43, 6, v2
	v_add_u32_e32 v4, 0x200, v2
	v_add_u32_e32 v5, 0x400, v2
	v_add_u32_e32 v7, 0x600, v2
	v_ashrrev_i32_e32 v48, 6, v8
	v_add_u32_e32 v8, 0xc00, v2
	v_add_u32_e32 v2, 0xe00, v2
	v_ashrrev_i32_e32 v44, 6, v4
	v_ashrrev_i32_e32 v45, 6, v5
	v_ashrrev_i32_e32 v46, 6, v7
	v_ashrrev_i32_e32 v49, 6, v8
	v_ashrrev_i32_e32 v50, 6, v2
	v_mul_lo_u32 v2, v43, s59
	v_mul_lo_u32 v8, v44, s59
	v_mul_lo_u32 v9, v45, s59
	v_mul_lo_u32 v10, v46, s59
	v_mul_lo_u32 v11, v47, s59
	v_mul_lo_u32 v12, v48, s59
	v_mul_lo_u32 v13, v49, s59
	v_ashrrev_i32_e32 v51, 3, v4
	v_ashrrev_i32_e32 v53, 3, v5
	v_ashrrev_i32_e32 v55, 3, v7
	v_mul_lo_u32 v4, v50, s59
	v_lshl_add_u32 v42, v34, 2, v6
	v_lshl_add_u32 v52, v51, 2, v6
	v_lshl_add_u32 v54, v53, 2, v6
	v_lshl_add_u32 v56, v55, 2, v6
	v_add_u32_e32 v57, v3, v2
	v_add_u32_e32 v58, v3, v8
	v_add_u32_e32 v59, v3, v9
	v_add_u32_e32 v60, v3, v10
	v_add_u32_e32 v61, v3, v11
	v_add_u32_e32 v62, v3, v12
	v_add_u32_e32 v63, v3, v13
	v_add_u32_e32 v64, v3, v4
	s_lshl_b32 s48, s98, 8
	s_mov_b32 s49, s98
	s_branch .Lwo_30
